# EpiResid: prefetch next residual-row batch into spare registers before current batch stores; counted vmcnt instead of vmcnt(0)
# speedup vs baseline: 1.0049x; 1.0049x over previous
.LBB0_780:
	s_lshr_b32 s1, s15, 1
	s_lshl_b32 s0, s0, 8
	s_and_b32 s1, s1, 0x60
	v_and_b32_e32 v98, 15, v96
	s_or_b32 s0, s1, s0
	v_lshrrev_b32_e32 v96, 2, v96
	v_and_or_b32 v96, v96, 12, s0
	s_lshl_b64 s[0:1], s[42:43], 12
	s_add_u32 s0, s40, s0
	s_addc_u32 s1, s41, s1
	s_lshr_b32 s6, s48, 12
	s_add_i32 s11, s6, 1
	s_and_b64 s[6:7], s[38:39], exec
	s_cselect_b32 s6, 0, s11
	s_mul_hi_u32 s7, s6, 0x6000
	s_mulk_i32 s6, 0x6000
	v_ashrrev_i32_e32 v97, 31, v96
	s_add_u32 s6, s2, s6
	s_addc_u32 s7, s22, s7
	v_lshlrev_b64 v[146:147], 2, v[96:97]
	v_lshl_add_u64 v[186:187], s[6:7], 0, v[146:147]
	s_ashr_i32 s6, s15, 2
	s_andn2_b32 s6, s6, 63
	v_or_b32_e32 v152, s6, v98
	v_ashrrev_i32_e32 v153, 31, v152
	v_lshl_add_u64 v[150:151], s[0:1], 0, v[146:147]
	v_lshlrev_b64 v[96:97], 12, v[152:153]
	v_lshl_add_u64 v[142:143], v[150:151], 0, v[96:97]
	v_or_b32_e32 v96, 16, v152
	v_ashrrev_i32_e32 v97, 31, v96
	v_lshlrev_b64 v[96:97], 12, v[96:97]
	s_add_i32 s6, s6, s10
	v_lshl_add_u64 v[96:97], v[150:151], 0, v[96:97]
	v_or_b32_e32 v148, s6, v98
	global_load_dwordx4 v[156:159], v[142:143], off nt
	global_load_dwordx4 v[160:163], v[142:143], off offset:64 nt
	global_load_dwordx4 v[166:169], v[142:143], off offset:512 nt
	global_load_dwordx4 v[170:173], v[142:143], off offset:576 nt
	global_load_dwordx4 v[174:177], v[96:97], off nt
	global_load_dwordx4 v[178:181], v[96:97], off offset:64 nt
	global_load_dwordx4 v[182:185], v[96:97], off offset:512 nt
	global_load_dwordx4 v[198:201], v[96:97], off offset:576 nt
	v_ashrrev_i32_e32 v149, 31, v148
	global_load_dwordx4 v[96:99], v[186:187], off
	global_load_dwordx4 v[202:205], v[186:187], off offset:64
	global_load_dwordx4 v[206:209], v[186:187], off offset:512
	global_load_dwordx4 v[210:213], v[186:187], off offset:576
	s_mov_b64 s[100:101], 0x20000
	v_lshl_add_u64 v[214:215], v[142:143], 0, s[100:101]
	global_load_dwordx4 v[218:221], v[214:215], off nt
	global_load_dwordx4 v[222:225], v[214:215], off offset:64 nt
	global_load_dwordx4 v[226:229], v[214:215], off offset:512 nt
	global_load_dwordx4 v[230:233], v[214:215], off offset:576 nt
	s_mov_b64 s[100:101], 0x30000
	v_lshl_add_u64 v[216:217], v[142:143], 0, s[100:101]
	global_load_dwordx4 v[240:243], v[216:217], off nt
	global_load_dwordx4 v[244:247], v[216:217], off offset:64 nt
	global_load_dwordx4 v[248:251], v[216:217], off offset:512 nt
	global_load_dwordx4 v[252:255], v[216:217], off offset:576 nt
	v_lshlrev_b64 v[144:145], 12, v[148:149]
	v_lshl_add_u64 v[144:145], s[4:5], 0, v[144:145]
	v_lshl_add_u64 v[144:145], v[144:145], 0, v[146:147]
	s_mov_b32 s0, 0x80000
	s_mov_b64 s[6:7], 0x80000
	s_mov_b32 s1, 0x90000
	s_mov_b64 s[10:11], 0x90000
	s_mov_b32 s67, 0xb0000
	s_mov_b64 s[38:39], s[20:21]
	s_waitcnt vmcnt(0)
	v_pk_fma_f32 v[158:159], v[102:103], v[98:99], v[158:159]
	v_pk_fma_f32 v[156:157], v[100:101], v[96:97], v[156:157]
	v_mov_b32_e32 v100, v202
	v_mov_b32_e32 v101, v203
	v_mov_b32_e32 v102, v204
	v_mov_b32_e32 v103, v205
	v_pk_fma_f32 v[162:163], v[106:107], v[102:103], v[162:163]
	v_pk_fma_f32 v[160:161], v[104:105], v[100:101], v[160:161]
	v_mov_b32_e32 v104, v206
	v_mov_b32_e32 v105, v207
	v_mov_b32_e32 v106, v208
	v_mov_b32_e32 v107, v209
	v_pk_fma_f32 v[168:169], v[110:111], v[106:107], v[168:169]
	v_pk_fma_f32 v[166:167], v[108:109], v[104:105], v[166:167]
	v_mov_b32_e32 v108, v210
	v_mov_b32_e32 v109, v211
	v_mov_b32_e32 v110, v212
	v_mov_b32_e32 v111, v213
	s_nop 0
	global_store_dwordx4 v[144:145], v[156:159], off nt
	global_store_dwordx4 v[144:145], v[160:163], off offset:64 nt
	global_store_dwordx4 v[144:145], v[166:169], off offset:512 nt
	v_pk_fma_f32 v[118:119], v[118:119], v[106:107], v[184:185]
	v_pk_fma_f32 v[116:117], v[116:117], v[104:105], v[182:183]
	v_or_b32_e32 v166, 32, v148
	v_ashrrev_i32_e32 v167, 31, v166
	v_lshlrev_b64 v[166:167], 12, v[166:167]
	v_lshl_add_u64 v[166:167], s[4:5], 0, v[166:167]
	v_lshl_add_u64 v[166:167], v[166:167], 0, v[146:147]
	v_pk_fma_f32 v[122:123], v[122:123], v[110:111], v[172:173]
	v_pk_fma_f32 v[120:121], v[120:121], v[108:109], v[170:171]
	global_store_dwordx4 v[144:145], v[120:123], off offset:576 nt
	v_pk_fma_f32 v[114:115], v[114:115], v[110:111], v[200:201]
	v_pk_fma_f32 v[112:113], v[112:113], v[108:109], v[198:199]
	v_or_b32_e32 v120, 16, v148
	v_ashrrev_i32_e32 v121, 31, v120
	v_lshlrev_b64 v[120:121], 12, v[120:121]
	v_lshl_add_u64 v[120:121], s[4:5], 0, v[120:121]
	v_lshl_add_u64 v[156:157], v[120:121], 0, v[146:147]
	global_store_dwordx4 v[156:157], v[112:115], off offset:576 nt
	v_pk_fma_f32 v[122:123], v[130:131], v[98:99], v[176:177]
	v_pk_fma_f32 v[120:121], v[128:129], v[96:97], v[174:175]
	v_or_b32_e32 v112, 32, v152
	v_ashrrev_i32_e32 v113, 31, v112
	global_store_dwordx4 v[156:157], v[120:123], off nt
	v_lshlrev_b64 v[112:113], 12, v[112:113]
	global_store_dwordx4 v[156:157], v[116:119], off offset:512 nt
	v_pk_fma_f32 v[122:123], v[126:127], v[102:103], v[180:181]
	v_pk_fma_f32 v[120:121], v[124:125], v[100:101], v[178:179]
	global_store_dwordx4 v[156:157], v[120:123], off offset:64 nt
	v_lshl_add_u64 v[124:125], v[150:151], 0, v[112:113]
	v_mov_b32_e32 v112, v218
	v_mov_b32_e32 v113, v219
	v_mov_b32_e32 v114, v220
	v_mov_b32_e32 v115, v221
	v_mov_b32_e32 v116, v222
	v_mov_b32_e32 v117, v223
	v_mov_b32_e32 v118, v224
	v_mov_b32_e32 v119, v225
	v_mov_b32_e32 v120, v226
	v_mov_b32_e32 v121, v227
	v_mov_b32_e32 v122, v228
	v_mov_b32_e32 v123, v229
	s_nop 0
	v_mov_b32_e32 v124, v230
	v_mov_b32_e32 v125, v231
	v_mov_b32_e32 v126, v232
	v_mov_b32_e32 v127, v233
	v_or_b32_e32 v128, 48, v152
	v_ashrrev_i32_e32 v129, 31, v128
	v_lshlrev_b64 v[128:129], 12, v[128:129]
	v_lshl_add_u64 v[160:161], v[150:151], 0, v[128:129]
	v_mov_b32_e32 v128, v240
	v_mov_b32_e32 v129, v241
	v_mov_b32_e32 v130, v242
	v_mov_b32_e32 v131, v243
	v_mov_b32_e32 v150, v244
	v_mov_b32_e32 v151, v245
	v_mov_b32_e32 v152, v246
	v_mov_b32_e32 v153, v247
	v_mov_b32_e32 v156, v248
	v_mov_b32_e32 v157, v249
	v_mov_b32_e32 v158, v250
	v_mov_b32_e32 v159, v251
	s_nop 0
	v_mov_b32_e32 v160, v252
	v_mov_b32_e32 v161, v253
	v_mov_b32_e32 v162, v254
	v_mov_b32_e32 v163, v255
	s_mov_b64 s[100:101], 0x80000
	v_lshl_add_u64 v[214:215], v[142:143], 0, s[100:101]
	global_load_dwordx4 v[218:221], v[214:215], off nt
	global_load_dwordx4 v[222:225], v[214:215], off offset:64 nt
	global_load_dwordx4 v[226:229], v[214:215], off offset:512 nt
	global_load_dwordx4 v[230:233], v[214:215], off offset:576 nt
	s_mov_b64 s[100:101], 0x90000
	v_lshl_add_u64 v[216:217], v[142:143], 0, s[100:101]
	global_load_dwordx4 v[240:243], v[216:217], off nt
	global_load_dwordx4 v[244:247], v[216:217], off offset:64 nt
	global_load_dwordx4 v[248:251], v[216:217], off offset:512 nt
	global_load_dwordx4 v[252:255], v[216:217], off offset:576 nt
	v_pk_fma_f32 v[94:95], v[94:95], v[98:99], v[114:115]
	v_pk_fma_f32 v[92:93], v[92:93], v[96:97], v[112:113]
	v_pk_fma_f32 v[90:91], v[90:91], v[102:103], v[118:119]
	v_pk_fma_f32 v[82:83], v[82:83], v[110:111], v[126:127]
	v_pk_fma_f32 v[80:81], v[80:81], v[108:109], v[124:125]
	global_store_dwordx4 v[166:167], v[80:83], off offset:576 nt
	v_pk_fma_f32 v[88:89], v[88:89], v[100:101], v[116:117]
	v_pk_fma_f32 v[86:87], v[86:87], v[106:107], v[122:123]
	v_or_b32_e32 v80, 48, v148
	v_ashrrev_i32_e32 v81, 31, v80
	v_lshlrev_b64 v[80:81], 12, v[80:81]
	v_lshl_add_u64 v[80:81], s[4:5], 0, v[80:81]
	v_lshl_add_u64 v[80:81], v[80:81], 0, v[146:147]
	v_pk_fma_f32 v[66:67], v[66:67], v[110:111], v[162:163]
	v_pk_fma_f32 v[64:65], v[64:65], v[108:109], v[160:161]
	global_store_dwordx4 v[80:81], v[64:67], off offset:576 nt
	v_pk_fma_f32 v[84:85], v[84:85], v[104:105], v[120:121]
	v_pk_fma_f32 v[78:79], v[78:79], v[98:99], v[130:131]
	v_add_co_u32_e32 v64, vcc, s0, v142
	v_pk_fma_f32 v[76:77], v[76:77], v[96:97], v[128:129]
	v_pk_fma_f32 v[74:75], v[74:75], v[102:103], v[152:153]
	v_pk_fma_f32 v[72:73], v[72:73], v[100:101], v[150:151]
	v_pk_fma_f32 v[70:71], v[70:71], v[106:107], v[158:159]
	v_pk_fma_f32 v[68:69], v[68:69], v[104:105], v[156:157]
	v_addc_co_u32_e32 v65, vcc, 0, v143, vcc
	global_store_dwordx4 v[166:167], v[92:95], off nt
	global_store_dwordx4 v[166:167], v[88:91], off offset:64 nt
	global_store_dwordx4 v[166:167], v[84:87], off offset:512 nt
	global_store_dwordx4 v[80:81], v[76:79], off nt
	global_store_dwordx4 v[80:81], v[72:75], off offset:64 nt
	global_store_dwordx4 v[80:81], v[68:71], off offset:512 nt
	v_lshl_add_u64 v[76:77], v[142:143], 0, s[6:7]
	v_add_co_u32_e32 v80, vcc, s1, v142
	s_waitcnt vmcnt(8)
	v_mov_b32_e32 v64, v218
	v_mov_b32_e32 v65, v219
	v_mov_b32_e32 v66, v220
	v_mov_b32_e32 v67, v221
	s_nop 0
	v_mov_b32_e32 v68, v222
	v_mov_b32_e32 v69, v223
	v_mov_b32_e32 v70, v224
	v_mov_b32_e32 v71, v225
	v_mov_b32_e32 v72, v226
	v_mov_b32_e32 v73, v227
	v_mov_b32_e32 v74, v228
	v_mov_b32_e32 v75, v229
	s_nop 0
	v_mov_b32_e32 v76, v230
	v_mov_b32_e32 v77, v231
	v_mov_b32_e32 v78, v232
	v_mov_b32_e32 v79, v233
	v_lshl_add_u64 v[92:93], v[142:143], 0, s[10:11]
	v_addc_co_u32_e32 v81, vcc, 0, v143, vcc
	v_mov_b32_e32 v80, v240
	v_mov_b32_e32 v81, v241
	v_mov_b32_e32 v82, v242
	v_mov_b32_e32 v83, v243
	s_nop 0
	v_mov_b32_e32 v84, v244
	v_mov_b32_e32 v85, v245
	v_mov_b32_e32 v86, v246
	v_mov_b32_e32 v87, v247
	v_mov_b32_e32 v88, v248
	v_mov_b32_e32 v89, v249
	v_mov_b32_e32 v90, v250
	v_mov_b32_e32 v91, v251
	s_nop 0
	v_mov_b32_e32 v92, v252
	v_mov_b32_e32 v93, v253
	v_mov_b32_e32 v94, v254
	v_mov_b32_e32 v95, v255
	s_mov_b64 s[100:101], 0xa0000
	v_lshl_add_u64 v[214:215], v[142:143], 0, s[100:101]
	global_load_dwordx4 v[218:221], v[214:215], off nt
	global_load_dwordx4 v[222:225], v[214:215], off offset:64 nt
	global_load_dwordx4 v[226:229], v[214:215], off offset:512 nt
	global_load_dwordx4 v[230:233], v[214:215], off offset:576 nt
	s_mov_b64 s[100:101], 0xb0000
	v_lshl_add_u64 v[216:217], v[142:143], 0, s[100:101]
	global_load_dwordx4 v[240:243], v[216:217], off nt
	global_load_dwordx4 v[244:247], v[216:217], off offset:64 nt
	global_load_dwordx4 v[248:251], v[216:217], off offset:512 nt
	global_load_dwordx4 v[252:255], v[216:217], off offset:576 nt
	v_lshl_add_u64 v[112:113], v[144:145], 0, s[6:7]
	s_mov_b64 s[6:7], 0xa0000
	v_pk_fma_f32 v[60:61], v[60:61], v[96:97], v[64:65]
	v_add_co_u32_e32 v64, vcc, s0, v144
	v_pk_fma_f32 v[46:47], v[46:47], v[106:107], v[74:75]
	s_nop 0
	v_addc_co_u32_e32 v65, vcc, 0, v145, vcc
	v_pk_fma_f32 v[44:45], v[44:45], v[104:105], v[72:73]
	global_store_dwordx4 v[112:113], v[44:47], off offset:512 nt
	v_pk_fma_f32 v[42:43], v[42:43], v[110:111], v[78:79]
	v_pk_fma_f32 v[40:41], v[40:41], v[108:109], v[76:77]
	v_add_co_u32_e32 v46, vcc, s1, v144
	global_store_dwordx4 v[112:113], v[40:43], off offset:576 nt
	v_lshl_add_u64 v[44:45], v[144:145], 0, s[10:11]
	v_addc_co_u32_e32 v47, vcc, 0, v145, vcc
	v_pk_fma_f32 v[42:43], v[54:55], v[98:99], v[82:83]
	v_pk_fma_f32 v[40:41], v[52:53], v[96:97], v[80:81]
	v_pk_fma_f32 v[34:35], v[34:35], v[110:111], v[94:95]
	v_pk_fma_f32 v[32:33], v[32:33], v[108:109], v[92:93]
	s_mov_b32 s0, 0xa0000
	v_pk_fma_f32 v[62:63], v[62:63], v[98:99], v[66:67]
	v_pk_fma_f32 v[58:59], v[58:59], v[102:103], v[70:71]
	v_pk_fma_f32 v[56:57], v[56:57], v[100:101], v[68:69]
	global_store_dwordx4 v[46:47], v[40:43], off nt
	v_pk_fma_f32 v[38:39], v[38:39], v[106:107], v[90:91]
	v_pk_fma_f32 v[36:37], v[36:37], v[104:105], v[88:89]
	v_pk_fma_f32 v[42:43], v[50:51], v[102:103], v[86:87]
	v_pk_fma_f32 v[40:41], v[48:49], v[100:101], v[84:85]
	global_store_dwordx4 v[44:45], v[32:35], off offset:576 nt
	global_store_dwordx4 v[64:65], v[60:63], off nt
	global_store_dwordx4 v[112:113], v[56:59], off offset:64 nt
	v_add_co_u32_e32 v32, vcc, s0, v142
	global_store_dwordx4 v[44:45], v[40:43], off offset:64 nt
	global_store_dwordx4 v[44:45], v[36:39], off offset:512 nt
	v_lshl_add_u64 v[44:45], v[142:143], 0, s[6:7]
	v_addc_co_u32_e32 v33, vcc, 0, v143, vcc
	s_mov_b32 s1, 0xb0000
	s_waitcnt vmcnt(8)
	v_mov_b32_e32 v32, v218
	v_mov_b32_e32 v33, v219
	v_mov_b32_e32 v34, v220
	v_mov_b32_e32 v35, v221
	s_nop 0
	v_mov_b32_e32 v36, v222
	v_mov_b32_e32 v37, v223
	v_mov_b32_e32 v38, v224
	v_mov_b32_e32 v39, v225
	v_mov_b32_e32 v40, v226
	v_mov_b32_e32 v41, v227
	v_mov_b32_e32 v42, v228
	v_mov_b32_e32 v43, v229
	s_nop 0
	v_mov_b32_e32 v44, v230
	v_mov_b32_e32 v45, v231
	v_mov_b32_e32 v46, v232
	v_mov_b32_e32 v47, v233
	s_mov_b64 s[10:11], 0xb0000
	v_add_co_u32_e32 v48, vcc, s1, v142
	v_lshl_add_u64 v[60:61], v[142:143], 0, s[10:11]
	s_nop 0
	v_addc_co_u32_e32 v49, vcc, 0, v143, vcc
	v_mov_b32_e32 v48, v240
	v_mov_b32_e32 v49, v241
	v_mov_b32_e32 v50, v242
	v_mov_b32_e32 v51, v243
	s_nop 0
	v_mov_b32_e32 v52, v244
	v_mov_b32_e32 v53, v245
	v_mov_b32_e32 v54, v246
	v_mov_b32_e32 v55, v247
	v_mov_b32_e32 v56, v248
	v_mov_b32_e32 v57, v249
	v_mov_b32_e32 v58, v250
	v_mov_b32_e32 v59, v251
	s_nop 0
	v_mov_b32_e32 v60, v252
	v_mov_b32_e32 v61, v253
	v_mov_b32_e32 v62, v254
	v_mov_b32_e32 v63, v255
	v_lshl_add_u64 v[64:65], v[144:145], 0, s[6:7]
	v_pk_fma_f32 v[28:29], v[28:29], v[96:97], v[32:33]
	v_add_co_u32_e32 v32, vcc, s0, v144
	v_pk_fma_f32 v[14:15], v[14:15], v[106:107], v[42:43]
	s_nop 0
	v_addc_co_u32_e32 v33, vcc, 0, v145, vcc
	v_pk_fma_f32 v[12:13], v[12:13], v[104:105], v[40:41]
	global_store_dwordx4 v[64:65], v[12:15], off offset:512 nt
	v_pk_fma_f32 v[10:11], v[10:11], v[110:111], v[46:47]
	v_pk_fma_f32 v[8:9], v[8:9], v[108:109], v[44:45]
	v_add_co_u32_e32 v14, vcc, s1, v144
	global_store_dwordx4 v[64:65], v[8:11], off offset:576 nt
	s_nop 0
	v_addc_co_u32_e32 v15, vcc, 0, v145, vcc
	v_pk_fma_f32 v[10:11], v[22:23], v[98:99], v[50:51]
	v_pk_fma_f32 v[8:9], v[20:21], v[96:97], v[48:49]
	v_pk_fma_f32 v[30:31], v[30:31], v[98:99], v[34:35]
	v_pk_fma_f32 v[26:27], v[26:27], v[102:103], v[38:39]
	v_pk_fma_f32 v[24:25], v[24:25], v[100:101], v[36:37]
	v_lshl_add_u64 v[12:13], v[144:145], 0, s[10:11]
	global_store_dwordx4 v[14:15], v[8:11], off nt
	v_pk_fma_f32 v[6:7], v[6:7], v[106:107], v[58:59]
	v_pk_fma_f32 v[4:5], v[4:5], v[104:105], v[56:57]
	v_pk_fma_f32 v[10:11], v[18:19], v[102:103], v[54:55]
	v_pk_fma_f32 v[8:9], v[16:17], v[100:101], v[52:53]
	v_pk_fma_f32 v[2:3], v[2:3], v[110:111], v[62:63]
	v_pk_fma_f32 v[0:1], v[0:1], v[108:109], v[60:61]
	s_and_b64 vcc, exec, s[36:37]
	s_mov_b32 s1, s14
	s_mov_b32 s0, s16
	s_mov_b64 s[10:11], s[30:31]
	global_store_dwordx4 v[32:33], v[28:31], off nt
	global_store_dwordx4 v[64:65], v[24:27], off offset:64 nt
	global_store_dwordx4 v[12:13], v[8:11], off offset:64 nt
	global_store_dwordx4 v[12:13], v[4:7], off offset:512 nt
	global_store_dwordx4 v[12:13], v[0:3], off offset:576 nt
	s_cbranch_vccnz .LBB0_797

.LBB0_1250:
	s_lshr_b32 s1, s15, 1
	s_lshl_b32 s0, s0, 8
	s_and_b32 s1, s1, 0x60
	v_and_b32_e32 v98, 15, v96
	s_or_b32 s0, s1, s0
	v_lshrrev_b32_e32 v96, 2, v96
	v_and_or_b32 v96, v96, 12, s0
	s_lshl_b64 s[0:1], s[40:41], 12
	s_add_u32 s0, s38, s0
	s_addc_u32 s1, s39, s1
	s_lshr_b32 s6, s48, 12
	s_add_i32 s11, s6, 1
	s_and_b64 s[6:7], s[36:37], exec
	s_cselect_b32 s6, 0, s11
	s_mul_hi_u32 s7, s6, 0x6000
	s_mulk_i32 s6, 0x6000
	v_ashrrev_i32_e32 v97, 31, v96
	s_add_u32 s6, s2, s6
	s_addc_u32 s7, s22, s7
	v_lshlrev_b64 v[146:147], 2, v[96:97]
	v_lshl_add_u64 v[186:187], s[6:7], 0, v[146:147]
	s_ashr_i32 s6, s15, 2
	s_andn2_b32 s6, s6, 63
	v_or_b32_e32 v152, s6, v98
	v_ashrrev_i32_e32 v153, 31, v152
	v_lshl_add_u64 v[150:151], s[0:1], 0, v[146:147]
	v_lshlrev_b64 v[96:97], 12, v[152:153]
	v_lshl_add_u64 v[142:143], v[150:151], 0, v[96:97]
	v_or_b32_e32 v96, 16, v152
	v_ashrrev_i32_e32 v97, 31, v96
	v_lshlrev_b64 v[96:97], 12, v[96:97]
	s_add_i32 s6, s6, s10
	v_lshl_add_u64 v[96:97], v[150:151], 0, v[96:97]
	v_or_b32_e32 v148, s6, v98
	global_load_dwordx4 v[156:159], v[142:143], off nt
	global_load_dwordx4 v[160:163], v[142:143], off offset:64 nt
	global_load_dwordx4 v[166:169], v[142:143], off offset:512 nt
	global_load_dwordx4 v[170:173], v[142:143], off offset:576 nt
	global_load_dwordx4 v[174:177], v[96:97], off nt
	global_load_dwordx4 v[178:181], v[96:97], off offset:64 nt
	global_load_dwordx4 v[182:185], v[96:97], off offset:512 nt
	global_load_dwordx4 v[198:201], v[96:97], off offset:576 nt
	v_ashrrev_i32_e32 v149, 31, v148
	global_load_dwordx4 v[96:99], v[186:187], off
	global_load_dwordx4 v[202:205], v[186:187], off offset:64
	global_load_dwordx4 v[206:209], v[186:187], off offset:512
	global_load_dwordx4 v[210:213], v[186:187], off offset:576
	s_mov_b64 s[100:101], 0x20000
	v_lshl_add_u64 v[214:215], v[142:143], 0, s[100:101]
	global_load_dwordx4 v[218:221], v[214:215], off nt
	global_load_dwordx4 v[222:225], v[214:215], off offset:64 nt
	global_load_dwordx4 v[226:229], v[214:215], off offset:512 nt
	global_load_dwordx4 v[230:233], v[214:215], off offset:576 nt
	s_mov_b64 s[100:101], 0x30000
	v_lshl_add_u64 v[216:217], v[142:143], 0, s[100:101]
	global_load_dwordx4 v[240:243], v[216:217], off nt
	global_load_dwordx4 v[244:247], v[216:217], off offset:64 nt
	global_load_dwordx4 v[248:251], v[216:217], off offset:512 nt
	global_load_dwordx4 v[252:255], v[216:217], off offset:576 nt
	v_lshlrev_b64 v[144:145], 12, v[148:149]
	v_lshl_add_u64 v[144:145], s[4:5], 0, v[144:145]
	v_lshl_add_u64 v[144:145], v[144:145], 0, v[146:147]
	s_mov_b32 s0, 0x80000
	s_mov_b64 s[6:7], 0x80000
	s_mov_b32 s1, 0x90000
	s_mov_b64 s[10:11], 0x90000
	s_mov_b32 s67, 0xb0000
	s_mov_b64 s[36:37], s[20:21]
	s_waitcnt vmcnt(0)
	v_pk_fma_f32 v[158:159], v[102:103], v[98:99], v[158:159]
	v_pk_fma_f32 v[156:157], v[100:101], v[96:97], v[156:157]
	v_mov_b32_e32 v100, v202
	v_mov_b32_e32 v101, v203
	v_mov_b32_e32 v102, v204
	v_mov_b32_e32 v103, v205
	v_pk_fma_f32 v[162:163], v[106:107], v[102:103], v[162:163]
	v_pk_fma_f32 v[160:161], v[104:105], v[100:101], v[160:161]
	v_mov_b32_e32 v104, v206
	v_mov_b32_e32 v105, v207
	v_mov_b32_e32 v106, v208
	v_mov_b32_e32 v107, v209
	v_pk_fma_f32 v[168:169], v[110:111], v[106:107], v[168:169]
	v_pk_fma_f32 v[166:167], v[108:109], v[104:105], v[166:167]
	v_mov_b32_e32 v108, v210
	v_mov_b32_e32 v109, v211
	v_mov_b32_e32 v110, v212
	v_mov_b32_e32 v111, v213
	s_nop 0
	global_store_dwordx4 v[144:145], v[156:159], off nt
	global_store_dwordx4 v[144:145], v[160:163], off offset:64 nt
	global_store_dwordx4 v[144:145], v[166:169], off offset:512 nt
	v_pk_fma_f32 v[118:119], v[118:119], v[106:107], v[184:185]
	v_pk_fma_f32 v[116:117], v[116:117], v[104:105], v[182:183]
	v_or_b32_e32 v166, 32, v148
	v_ashrrev_i32_e32 v167, 31, v166
	v_lshlrev_b64 v[166:167], 12, v[166:167]
	v_lshl_add_u64 v[166:167], s[4:5], 0, v[166:167]
	v_lshl_add_u64 v[166:167], v[166:167], 0, v[146:147]
	v_pk_fma_f32 v[122:123], v[122:123], v[110:111], v[172:173]
	v_pk_fma_f32 v[120:121], v[120:121], v[108:109], v[170:171]
	global_store_dwordx4 v[144:145], v[120:123], off offset:576 nt
	v_pk_fma_f32 v[114:115], v[114:115], v[110:111], v[200:201]
	v_pk_fma_f32 v[112:113], v[112:113], v[108:109], v[198:199]
	v_or_b32_e32 v120, 16, v148
	v_ashrrev_i32_e32 v121, 31, v120
	v_lshlrev_b64 v[120:121], 12, v[120:121]
	v_lshl_add_u64 v[120:121], s[4:5], 0, v[120:121]
	v_lshl_add_u64 v[156:157], v[120:121], 0, v[146:147]
	global_store_dwordx4 v[156:157], v[112:115], off offset:576 nt
	v_pk_fma_f32 v[122:123], v[130:131], v[98:99], v[176:177]
	v_pk_fma_f32 v[120:121], v[128:129], v[96:97], v[174:175]
	v_or_b32_e32 v112, 32, v152
	v_ashrrev_i32_e32 v113, 31, v112
	global_store_dwordx4 v[156:157], v[120:123], off nt
	v_lshlrev_b64 v[112:113], 12, v[112:113]
	global_store_dwordx4 v[156:157], v[116:119], off offset:512 nt
	v_pk_fma_f32 v[122:123], v[126:127], v[102:103], v[180:181]
	v_pk_fma_f32 v[120:121], v[124:125], v[100:101], v[178:179]
	global_store_dwordx4 v[156:157], v[120:123], off offset:64 nt
	v_lshl_add_u64 v[124:125], v[150:151], 0, v[112:113]
	v_mov_b32_e32 v112, v218
	v_mov_b32_e32 v113, v219
	v_mov_b32_e32 v114, v220
	v_mov_b32_e32 v115, v221
	v_mov_b32_e32 v116, v222
	v_mov_b32_e32 v117, v223
	v_mov_b32_e32 v118, v224
	v_mov_b32_e32 v119, v225
	v_mov_b32_e32 v120, v226
	v_mov_b32_e32 v121, v227
	v_mov_b32_e32 v122, v228
	v_mov_b32_e32 v123, v229
	s_nop 0
	v_mov_b32_e32 v124, v230
	v_mov_b32_e32 v125, v231
	v_mov_b32_e32 v126, v232
	v_mov_b32_e32 v127, v233
	v_or_b32_e32 v128, 48, v152
	v_ashrrev_i32_e32 v129, 31, v128
	v_lshlrev_b64 v[128:129], 12, v[128:129]
	v_lshl_add_u64 v[160:161], v[150:151], 0, v[128:129]
	v_mov_b32_e32 v128, v240
	v_mov_b32_e32 v129, v241
	v_mov_b32_e32 v130, v242
	v_mov_b32_e32 v131, v243
	v_mov_b32_e32 v150, v244
	v_mov_b32_e32 v151, v245
	v_mov_b32_e32 v152, v246
	v_mov_b32_e32 v153, v247
	v_mov_b32_e32 v156, v248
	v_mov_b32_e32 v157, v249
	v_mov_b32_e32 v158, v250
	v_mov_b32_e32 v159, v251
	s_nop 0
	v_mov_b32_e32 v160, v252
	v_mov_b32_e32 v161, v253
	v_mov_b32_e32 v162, v254
	v_mov_b32_e32 v163, v255
	s_mov_b64 s[100:101], 0x80000
	v_lshl_add_u64 v[214:215], v[142:143], 0, s[100:101]
	global_load_dwordx4 v[218:221], v[214:215], off nt
	global_load_dwordx4 v[222:225], v[214:215], off offset:64 nt
	global_load_dwordx4 v[226:229], v[214:215], off offset:512 nt
	global_load_dwordx4 v[230:233], v[214:215], off offset:576 nt
	s_mov_b64 s[100:101], 0x90000
	v_lshl_add_u64 v[216:217], v[142:143], 0, s[100:101]
	global_load_dwordx4 v[240:243], v[216:217], off nt
	global_load_dwordx4 v[244:247], v[216:217], off offset:64 nt
	global_load_dwordx4 v[248:251], v[216:217], off offset:512 nt
	global_load_dwordx4 v[252:255], v[216:217], off offset:576 nt
	v_pk_fma_f32 v[94:95], v[94:95], v[98:99], v[114:115]
	v_pk_fma_f32 v[92:93], v[92:93], v[96:97], v[112:113]
	v_pk_fma_f32 v[90:91], v[90:91], v[102:103], v[118:119]
	v_pk_fma_f32 v[82:83], v[82:83], v[110:111], v[126:127]
	v_pk_fma_f32 v[80:81], v[80:81], v[108:109], v[124:125]
	global_store_dwordx4 v[166:167], v[80:83], off offset:576 nt
	v_pk_fma_f32 v[88:89], v[88:89], v[100:101], v[116:117]
	v_pk_fma_f32 v[86:87], v[86:87], v[106:107], v[122:123]
	v_or_b32_e32 v80, 48, v148
	v_ashrrev_i32_e32 v81, 31, v80
	v_lshlrev_b64 v[80:81], 12, v[80:81]
	v_lshl_add_u64 v[80:81], s[4:5], 0, v[80:81]
	v_lshl_add_u64 v[80:81], v[80:81], 0, v[146:147]
	v_pk_fma_f32 v[66:67], v[66:67], v[110:111], v[162:163]
	v_pk_fma_f32 v[64:65], v[64:65], v[108:109], v[160:161]
	global_store_dwordx4 v[80:81], v[64:67], off offset:576 nt
	v_pk_fma_f32 v[84:85], v[84:85], v[104:105], v[120:121]
	v_pk_fma_f32 v[78:79], v[78:79], v[98:99], v[130:131]
	v_add_co_u32_e32 v64, vcc, s0, v142
	v_pk_fma_f32 v[76:77], v[76:77], v[96:97], v[128:129]
	v_pk_fma_f32 v[74:75], v[74:75], v[102:103], v[152:153]
	v_pk_fma_f32 v[72:73], v[72:73], v[100:101], v[150:151]
	v_pk_fma_f32 v[70:71], v[70:71], v[106:107], v[158:159]
	v_pk_fma_f32 v[68:69], v[68:69], v[104:105], v[156:157]
	v_addc_co_u32_e32 v65, vcc, 0, v143, vcc
	global_store_dwordx4 v[166:167], v[92:95], off nt
	global_store_dwordx4 v[166:167], v[88:91], off offset:64 nt
	global_store_dwordx4 v[166:167], v[84:87], off offset:512 nt
	global_store_dwordx4 v[80:81], v[76:79], off nt
	global_store_dwordx4 v[80:81], v[72:75], off offset:64 nt
	global_store_dwordx4 v[80:81], v[68:71], off offset:512 nt
	v_lshl_add_u64 v[76:77], v[142:143], 0, s[6:7]
	v_add_co_u32_e32 v80, vcc, s1, v142
	s_waitcnt vmcnt(8)
	v_mov_b32_e32 v64, v218
	v_mov_b32_e32 v65, v219
	v_mov_b32_e32 v66, v220
	v_mov_b32_e32 v67, v221
	s_nop 0
	v_mov_b32_e32 v68, v222
	v_mov_b32_e32 v69, v223
	v_mov_b32_e32 v70, v224
	v_mov_b32_e32 v71, v225
	v_mov_b32_e32 v72, v226
	v_mov_b32_e32 v73, v227
	v_mov_b32_e32 v74, v228
	v_mov_b32_e32 v75, v229
	s_nop 0
	v_mov_b32_e32 v76, v230
	v_mov_b32_e32 v77, v231
	v_mov_b32_e32 v78, v232
	v_mov_b32_e32 v79, v233
	v_lshl_add_u64 v[92:93], v[142:143], 0, s[10:11]
	v_addc_co_u32_e32 v81, vcc, 0, v143, vcc
	v_mov_b32_e32 v80, v240
	v_mov_b32_e32 v81, v241
	v_mov_b32_e32 v82, v242
	v_mov_b32_e32 v83, v243
	s_nop 0
	v_mov_b32_e32 v84, v244
	v_mov_b32_e32 v85, v245
	v_mov_b32_e32 v86, v246
	v_mov_b32_e32 v87, v247
	v_mov_b32_e32 v88, v248
	v_mov_b32_e32 v89, v249
	v_mov_b32_e32 v90, v250
	v_mov_b32_e32 v91, v251
	s_nop 0
	v_mov_b32_e32 v92, v252
	v_mov_b32_e32 v93, v253
	v_mov_b32_e32 v94, v254
	v_mov_b32_e32 v95, v255
	s_mov_b64 s[100:101], 0xa0000
	v_lshl_add_u64 v[214:215], v[142:143], 0, s[100:101]
	global_load_dwordx4 v[218:221], v[214:215], off nt
	global_load_dwordx4 v[222:225], v[214:215], off offset:64 nt
	global_load_dwordx4 v[226:229], v[214:215], off offset:512 nt
	global_load_dwordx4 v[230:233], v[214:215], off offset:576 nt
	s_mov_b64 s[100:101], 0xb0000
	v_lshl_add_u64 v[216:217], v[142:143], 0, s[100:101]
	global_load_dwordx4 v[240:243], v[216:217], off nt
	global_load_dwordx4 v[244:247], v[216:217], off offset:64 nt
	global_load_dwordx4 v[248:251], v[216:217], off offset:512 nt
	global_load_dwordx4 v[252:255], v[216:217], off offset:576 nt
	v_lshl_add_u64 v[112:113], v[144:145], 0, s[6:7]
	s_mov_b64 s[6:7], 0xa0000
	v_pk_fma_f32 v[60:61], v[60:61], v[96:97], v[64:65]
	v_add_co_u32_e32 v64, vcc, s0, v144
	v_pk_fma_f32 v[46:47], v[46:47], v[106:107], v[74:75]
	s_nop 0
	v_addc_co_u32_e32 v65, vcc, 0, v145, vcc
	v_pk_fma_f32 v[44:45], v[44:45], v[104:105], v[72:73]
	global_store_dwordx4 v[112:113], v[44:47], off offset:512 nt
	v_pk_fma_f32 v[42:43], v[42:43], v[110:111], v[78:79]
	v_pk_fma_f32 v[40:41], v[40:41], v[108:109], v[76:77]
	v_add_co_u32_e32 v46, vcc, s1, v144
	global_store_dwordx4 v[112:113], v[40:43], off offset:576 nt
	v_lshl_add_u64 v[44:45], v[144:145], 0, s[10:11]
	v_addc_co_u32_e32 v47, vcc, 0, v145, vcc
	v_pk_fma_f32 v[42:43], v[54:55], v[98:99], v[82:83]
	v_pk_fma_f32 v[40:41], v[52:53], v[96:97], v[80:81]
	v_pk_fma_f32 v[34:35], v[34:35], v[110:111], v[94:95]
	v_pk_fma_f32 v[32:33], v[32:33], v[108:109], v[92:93]
	s_mov_b32 s0, 0xa0000
	v_pk_fma_f32 v[62:63], v[62:63], v[98:99], v[66:67]
	v_pk_fma_f32 v[58:59], v[58:59], v[102:103], v[70:71]
	v_pk_fma_f32 v[56:57], v[56:57], v[100:101], v[68:69]
	global_store_dwordx4 v[46:47], v[40:43], off nt
	v_pk_fma_f32 v[38:39], v[38:39], v[106:107], v[90:91]
	v_pk_fma_f32 v[36:37], v[36:37], v[104:105], v[88:89]
	v_pk_fma_f32 v[42:43], v[50:51], v[102:103], v[86:87]
	v_pk_fma_f32 v[40:41], v[48:49], v[100:101], v[84:85]
	global_store_dwordx4 v[44:45], v[32:35], off offset:576 nt
	global_store_dwordx4 v[64:65], v[60:63], off nt
	global_store_dwordx4 v[112:113], v[56:59], off offset:64 nt
	v_add_co_u32_e32 v32, vcc, s0, v142
	global_store_dwordx4 v[44:45], v[40:43], off offset:64 nt
	global_store_dwordx4 v[44:45], v[36:39], off offset:512 nt
	v_lshl_add_u64 v[44:45], v[142:143], 0, s[6:7]
	v_addc_co_u32_e32 v33, vcc, 0, v143, vcc
	s_mov_b32 s1, 0xb0000
	s_waitcnt vmcnt(8)
	v_mov_b32_e32 v32, v218
	v_mov_b32_e32 v33, v219
	v_mov_b32_e32 v34, v220
	v_mov_b32_e32 v35, v221
	s_nop 0
	v_mov_b32_e32 v36, v222
	v_mov_b32_e32 v37, v223
	v_mov_b32_e32 v38, v224
	v_mov_b32_e32 v39, v225
	v_mov_b32_e32 v40, v226
	v_mov_b32_e32 v41, v227
	v_mov_b32_e32 v42, v228
	v_mov_b32_e32 v43, v229
	s_nop 0
	v_mov_b32_e32 v44, v230
	v_mov_b32_e32 v45, v231
	v_mov_b32_e32 v46, v232
	v_mov_b32_e32 v47, v233
	s_mov_b64 s[10:11], 0xb0000
	v_add_co_u32_e32 v48, vcc, s1, v142
	v_lshl_add_u64 v[60:61], v[142:143], 0, s[10:11]
	s_nop 0
	v_addc_co_u32_e32 v49, vcc, 0, v143, vcc
	v_mov_b32_e32 v48, v240
	v_mov_b32_e32 v49, v241
	v_mov_b32_e32 v50, v242
	v_mov_b32_e32 v51, v243
	s_nop 0
	v_mov_b32_e32 v52, v244
	v_mov_b32_e32 v53, v245
	v_mov_b32_e32 v54, v246
	v_mov_b32_e32 v55, v247
	v_mov_b32_e32 v56, v248
	v_mov_b32_e32 v57, v249
	v_mov_b32_e32 v58, v250
	v_mov_b32_e32 v59, v251
	s_nop 0
	v_mov_b32_e32 v60, v252
	v_mov_b32_e32 v61, v253
	v_mov_b32_e32 v62, v254
	v_mov_b32_e32 v63, v255
	v_lshl_add_u64 v[64:65], v[144:145], 0, s[6:7]
	v_pk_fma_f32 v[28:29], v[28:29], v[96:97], v[32:33]
	v_add_co_u32_e32 v32, vcc, s0, v144
	v_pk_fma_f32 v[14:15], v[14:15], v[106:107], v[42:43]
	s_nop 0
	v_addc_co_u32_e32 v33, vcc, 0, v145, vcc
	v_pk_fma_f32 v[12:13], v[12:13], v[104:105], v[40:41]
	global_store_dwordx4 v[64:65], v[12:15], off offset:512 nt
	v_pk_fma_f32 v[10:11], v[10:11], v[110:111], v[46:47]
	v_pk_fma_f32 v[8:9], v[8:9], v[108:109], v[44:45]
	v_add_co_u32_e32 v14, vcc, s1, v144
	global_store_dwordx4 v[64:65], v[8:11], off offset:576 nt
	s_nop 0
	v_addc_co_u32_e32 v15, vcc, 0, v145, vcc
	v_pk_fma_f32 v[10:11], v[22:23], v[98:99], v[50:51]
	v_pk_fma_f32 v[8:9], v[20:21], v[96:97], v[48:49]
	v_pk_fma_f32 v[30:31], v[30:31], v[98:99], v[34:35]
	v_pk_fma_f32 v[26:27], v[26:27], v[102:103], v[38:39]
	v_pk_fma_f32 v[24:25], v[24:25], v[100:101], v[36:37]
	v_lshl_add_u64 v[12:13], v[144:145], 0, s[10:11]
	global_store_dwordx4 v[14:15], v[8:11], off nt
	v_pk_fma_f32 v[6:7], v[6:7], v[106:107], v[58:59]
	v_pk_fma_f32 v[4:5], v[4:5], v[104:105], v[56:57]
	v_pk_fma_f32 v[10:11], v[18:19], v[102:103], v[54:55]
	v_pk_fma_f32 v[8:9], v[16:17], v[100:101], v[52:53]
	v_pk_fma_f32 v[2:3], v[2:3], v[110:111], v[62:63]
	v_pk_fma_f32 v[0:1], v[0:1], v[108:109], v[60:61]
	s_and_b64 vcc, exec, s[34:35]
	s_mov_b32 s1, s14
	s_mov_b32 s0, s16
	s_mov_b64 s[10:11], s[30:31]
	global_store_dwordx4 v[32:33], v[28:31], off nt
	global_store_dwordx4 v[64:65], v[24:27], off offset:64 nt
	global_store_dwordx4 v[12:13], v[8:11], off offset:64 nt
	global_store_dwordx4 v[12:13], v[4:7], off offset:512 nt
	global_store_dwordx4 v[12:13], v[0:3], off offset:576 nt
	s_cbranch_vccnz .LBB0_1267

.LBB0_1549:
	s_add_u32 s14, s10, 0x4000
	s_addc_u32 s15, s11, 0
	s_cmp_eq_u32 s51, 40
	s_cselect_b32 s20, s4, s14
	s_cselect_b32 s21, s5, s15
	s_cselect_b32 s14, s8, s48
	s_cselect_b32 s15, s9, s50
	s_add_u32 s16, s20, 0x8000
	s_addc_u32 s17, s21, 0
	s_add_i32 s52, 0, 0x10000
	v_add_u32_e32 v146, s52, v150
	ds_read_b128 v[96:99], v146
	ds_read_b128 v[138:141], v146 offset:1024
	ds_read_b128 v[142:145], v146 offset:2048
	ds_read_b128 v[146:149], v146 offset:3072
	v_lshl_add_u64 v[186:187], s[10:11], 0, v[134:135]
	s_add_i32 m0, s37, 0xc000
	ds_read_b128 v[152:155], v151
	ds_read_b128 v[156:159], v151 offset:1024
	ds_read_b128 v[160:163], v151 offset:2048
	ds_read_b128 v[166:169], v151 offset:3072
	ds_read_b128 v[170:173], v151 offset:4096
	ds_read_b128 v[174:177], v151 offset:5120
	ds_read_b128 v[178:181], v151 offset:6144
	ds_read_b128 v[182:185], v151 offset:7168
	global_load_lds_dwordx4 v[186:187], off
	v_lshl_add_u64 v[186:187], s[10:11], 0, v[136:137]
	s_add_i32 m0, s37, 0xe000
	s_nop 0
	global_load_lds_dwordx4 v[186:187], off
	s_waitcnt lgkmcnt(8)
	s_barrier
	s_waitcnt lgkmcnt(0)
	s_setprio 1
	s_waitcnt lgkmcnt(0)
	v_mfma_f32_16x16x32_bf16 v[100:103], v[96:99], v[152:155], v[100:103]
	v_mfma_f32_16x16x32_bf16 v[104:107], v[142:145], v[152:155], v[104:107]
	v_mfma_f32_16x16x32_bf16 v[128:131], v[96:99], v[160:163], v[128:131]
	v_mfma_f32_16x16x32_bf16 v[124:127], v[142:145], v[160:163], v[124:127]
	v_mfma_f32_16x16x32_bf16 v[92:95], v[96:99], v[170:173], v[92:95]
	v_mfma_f32_16x16x32_bf16 v[88:91], v[142:145], v[170:173], v[88:91]
	v_mfma_f32_16x16x32_bf16 v[76:79], v[96:99], v[178:181], v[76:79]
	v_mfma_f32_16x16x32_bf16 v[72:75], v[142:145], v[178:181], v[72:75]
	v_mfma_f32_16x16x32_bf16 v[100:103], v[138:141], v[156:159], v[100:103]
	v_mfma_f32_16x16x32_bf16 v[104:107], v[146:149], v[156:159], v[104:107]
	v_mfma_f32_16x16x32_bf16 v[128:131], v[138:141], v[166:169], v[128:131]
	v_mfma_f32_16x16x32_bf16 v[124:127], v[146:149], v[166:169], v[124:127]
	v_mfma_f32_16x16x32_bf16 v[92:95], v[138:141], v[174:177], v[92:95]
	v_mfma_f32_16x16x32_bf16 v[88:91], v[146:149], v[174:177], v[88:91]
	v_mfma_f32_16x16x32_bf16 v[76:79], v[138:141], v[182:185], v[76:79]
	v_mfma_f32_16x16x32_bf16 v[72:75], v[146:149], v[182:185], v[72:75]
	s_setprio 0
	s_barrier
	s_add_i32 s58, 0, 0x14000
	v_add_u32_e32 v186, s58, v150
	s_add_i32 s52, s52, s36
	ds_read_b128 v[198:201], v186
	ds_read_b128 v[202:205], v186 offset:1024
	ds_read_b128 v[206:209], v186 offset:2048
	ds_read_b128 v[210:213], v186 offset:3072
	v_lshl_add_u64 v[186:187], s[14:15], 0, v[164:165]
	s_mov_b32 m0, s52
	s_nop 0
	global_load_lds_dwordx4 v[186:187], off
	v_lshl_add_u64 v[186:187], s[14:15], 0, v[132:133]
	s_add_i32 m0, s52, 0x2000
	s_nop 0
	global_load_lds_dwordx4 v[186:187], off
	s_barrier
	s_waitcnt lgkmcnt(0)
	s_setprio 1
	s_waitcnt lgkmcnt(0)
	v_mfma_f32_16x16x32_bf16 v[108:111], v[198:201], v[152:155], v[108:111]
	v_mfma_f32_16x16x32_bf16 v[120:123], v[206:209], v[152:155], v[120:123]
	v_mfma_f32_16x16x32_bf16 v[116:119], v[198:201], v[160:163], v[116:119]
	v_mfma_f32_16x16x32_bf16 v[112:115], v[206:209], v[160:163], v[112:115]
	v_mfma_f32_16x16x32_bf16 v[84:87], v[198:201], v[170:173], v[84:87]
	v_mfma_f32_16x16x32_bf16 v[80:83], v[206:209], v[170:173], v[80:83]
	v_mfma_f32_16x16x32_bf16 v[68:71], v[198:201], v[178:181], v[68:71]
	v_mfma_f32_16x16x32_bf16 v[64:67], v[206:209], v[178:181], v[64:67]
	v_mfma_f32_16x16x32_bf16 v[108:111], v[202:205], v[156:159], v[108:111]
	v_mfma_f32_16x16x32_bf16 v[120:123], v[210:213], v[156:159], v[120:123]
	v_mfma_f32_16x16x32_bf16 v[116:119], v[202:205], v[166:169], v[116:119]
	v_mfma_f32_16x16x32_bf16 v[112:115], v[210:213], v[166:169], v[112:115]
	v_mfma_f32_16x16x32_bf16 v[84:87], v[202:205], v[174:177], v[84:87]
	v_mfma_f32_16x16x32_bf16 v[80:83], v[210:213], v[174:177], v[80:83]
	v_mfma_f32_16x16x32_bf16 v[68:71], v[202:205], v[182:185], v[68:71]
	v_mfma_f32_16x16x32_bf16 v[64:67], v[210:213], v[182:185], v[64:67]
	s_setprio 0
	s_mov_b32 m0, s37
	v_lshl_add_u64 v[186:187], s[20:21], 0, v[164:165]
	s_barrier
	ds_read_b128 v[152:155], v151 offset:16384
	ds_read_b128 v[156:159], v151 offset:17408
	ds_read_b128 v[160:163], v151 offset:18432
	ds_read_b128 v[166:169], v151 offset:19456
	ds_read_b128 v[170:173], v151 offset:20480
	ds_read_b128 v[174:177], v151 offset:21504
	ds_read_b128 v[178:181], v151 offset:22528
	ds_read_b128 v[182:185], v151 offset:23552
	global_load_lds_dwordx4 v[186:187], off
	v_lshl_add_u64 v[186:187], s[20:21], 0, v[132:133]
	s_mov_b32 m0, s38
	s_nop 0
	global_load_lds_dwordx4 v[186:187], off
	s_barrier
	s_waitcnt lgkmcnt(0)
	s_setprio 1
	s_waitcnt lgkmcnt(0)
	v_mfma_f32_16x16x32_bf16 v[60:63], v[96:99], v[152:155], v[60:63]
	v_mfma_f32_16x16x32_bf16 v[56:59], v[142:145], v[152:155], v[56:59]
	v_mfma_f32_16x16x32_bf16 v[52:55], v[96:99], v[160:163], v[52:55]
	v_mfma_f32_16x16x32_bf16 v[48:51], v[142:145], v[160:163], v[48:51]
	v_mfma_f32_16x16x32_bf16 v[28:31], v[96:99], v[170:173], v[28:31]
	v_mfma_f32_16x16x32_bf16 v[24:27], v[142:145], v[170:173], v[24:27]
	v_mfma_f32_16x16x32_bf16 v[20:23], v[96:99], v[178:181], v[20:23]
	v_mfma_f32_16x16x32_bf16 v[16:19], v[142:145], v[178:181], v[16:19]
	v_mfma_f32_16x16x32_bf16 v[60:63], v[138:141], v[156:159], v[60:63]
	v_mfma_f32_16x16x32_bf16 v[56:59], v[146:149], v[156:159], v[56:59]
	v_mfma_f32_16x16x32_bf16 v[52:55], v[138:141], v[166:169], v[52:55]
	v_mfma_f32_16x16x32_bf16 v[48:51], v[146:149], v[166:169], v[48:51]
	v_mfma_f32_16x16x32_bf16 v[28:31], v[138:141], v[174:177], v[28:31]
	v_mfma_f32_16x16x32_bf16 v[24:27], v[146:149], v[174:177], v[24:27]
	v_mfma_f32_16x16x32_bf16 v[20:23], v[138:141], v[182:185], v[20:23]
	v_mfma_f32_16x16x32_bf16 v[16:19], v[146:149], v[182:185], v[16:19]
	s_setprio 0
	s_barrier
	s_add_u32 s52, s14, 0x4000
	s_addc_u32 s53, s15, 0
	s_add_i32 s58, s58, s36
	v_lshl_add_u64 v[96:97], s[52:53], 0, v[164:165]
	s_mov_b32 m0, s58
	s_nop 0
	global_load_lds_dwordx4 v[96:97], off
	v_lshl_add_u64 v[96:97], s[52:53], 0, v[132:133]
	s_add_i32 m0, s58, 0x2000
	s_nop 0
	global_load_lds_dwordx4 v[96:97], off
	s_waitcnt vmcnt(6)
	s_barrier
	s_setprio 1
	v_mfma_f32_16x16x32_bf16 v[44:47], v[198:201], v[152:155], v[44:47]
	v_mfma_f32_16x16x32_bf16 v[40:43], v[206:209], v[152:155], v[40:43]
	v_mfma_f32_16x16x32_bf16 v[36:39], v[198:201], v[160:163], v[36:39]
	v_mfma_f32_16x16x32_bf16 v[32:35], v[206:209], v[160:163], v[32:35]
	v_mfma_f32_16x16x32_bf16 v[12:15], v[198:201], v[170:173], v[12:15]
	v_mfma_f32_16x16x32_bf16 v[8:11], v[206:209], v[170:173], v[8:11]
	v_mfma_f32_16x16x32_bf16 v[4:7], v[198:201], v[178:181], v[4:7]
	v_mfma_f32_16x16x32_bf16 v[0:3], v[206:209], v[178:181], v[0:3]
	v_mfma_f32_16x16x32_bf16 v[44:47], v[202:205], v[156:159], v[44:47]
	v_mfma_f32_16x16x32_bf16 v[40:43], v[210:213], v[156:159], v[40:43]
	v_mfma_f32_16x16x32_bf16 v[36:39], v[202:205], v[166:169], v[36:39]
	v_mfma_f32_16x16x32_bf16 v[32:35], v[210:213], v[166:169], v[32:35]
	v_mfma_f32_16x16x32_bf16 v[12:15], v[202:205], v[174:177], v[12:15]
	v_mfma_f32_16x16x32_bf16 v[8:11], v[210:213], v[174:177], v[8:11]
	v_mfma_f32_16x16x32_bf16 v[4:7], v[202:205], v[182:185], v[4:7]
	v_mfma_f32_16x16x32_bf16 v[0:3], v[210:213], v[182:185], v[0:3]
	s_setprio 0
	s_add_i32 s52, 0, 0x18000
	v_add_u32_e32 v146, s52, v150
	s_barrier
	ds_read_b128 v[96:99], v146
	ds_read_b128 v[138:141], v146 offset:1024
	ds_read_b128 v[142:145], v146 offset:2048
	ds_read_b128 v[146:149], v146 offset:3072
	s_add_u32 s20, s20, 0x4000
	s_addc_u32 s21, s21, 0
	s_mov_b32 m0, s39
	v_lshl_add_u64 v[186:187], s[20:21], 0, v[164:165]
	ds_read_b128 v[152:155], v151 offset:32768
	ds_read_b128 v[156:159], v151 offset:33792
	ds_read_b128 v[160:163], v151 offset:34816
	ds_read_b128 v[166:169], v151 offset:35840
	ds_read_b128 v[170:173], v151 offset:36864
	ds_read_b128 v[174:177], v151 offset:37888
	ds_read_b128 v[178:181], v151 offset:38912
	ds_read_b128 v[182:185], v151 offset:39936
	global_load_lds_dwordx4 v[186:187], off
	v_lshl_add_u64 v[186:187], s[20:21], 0, v[132:133]
	s_mov_b32 m0, s40
	s_nop 0
	global_load_lds_dwordx4 v[186:187], off
	s_waitcnt lgkmcnt(8)
	s_barrier
	s_waitcnt lgkmcnt(0)
	s_setprio 1
	s_waitcnt lgkmcnt(0)
	v_mfma_f32_16x16x32_bf16 v[100:103], v[96:99], v[152:155], v[100:103]
	v_mfma_f32_16x16x32_bf16 v[104:107], v[142:145], v[152:155], v[104:107]
	v_mfma_f32_16x16x32_bf16 v[128:131], v[96:99], v[160:163], v[128:131]
	v_mfma_f32_16x16x32_bf16 v[124:127], v[142:145], v[160:163], v[124:127]
	v_mfma_f32_16x16x32_bf16 v[92:95], v[96:99], v[170:173], v[92:95]
	v_mfma_f32_16x16x32_bf16 v[88:91], v[142:145], v[170:173], v[88:91]
	v_mfma_f32_16x16x32_bf16 v[76:79], v[96:99], v[178:181], v[76:79]
	v_mfma_f32_16x16x32_bf16 v[72:75], v[142:145], v[178:181], v[72:75]
	v_mfma_f32_16x16x32_bf16 v[100:103], v[138:141], v[156:159], v[100:103]
	v_mfma_f32_16x16x32_bf16 v[104:107], v[146:149], v[156:159], v[104:107]
	v_mfma_f32_16x16x32_bf16 v[128:131], v[138:141], v[166:169], v[128:131]
	v_mfma_f32_16x16x32_bf16 v[124:127], v[146:149], v[166:169], v[124:127]
	v_mfma_f32_16x16x32_bf16 v[92:95], v[138:141], v[174:177], v[92:95]
	v_mfma_f32_16x16x32_bf16 v[88:91], v[146:149], v[174:177], v[88:91]
	v_mfma_f32_16x16x32_bf16 v[76:79], v[138:141], v[182:185], v[76:79]
	v_mfma_f32_16x16x32_bf16 v[72:75], v[146:149], v[182:185], v[72:75]
	s_setprio 0
	s_barrier
	s_add_i32 s53, 0, 0x1c000
	s_add_u32 s20, s14, 0x8000
	v_add_u32_e32 v186, s53, v150
	s_addc_u32 s21, s15, 0
	s_add_i32 s52, s52, s36
	ds_read_b128 v[198:201], v186
	ds_read_b128 v[202:205], v186 offset:1024
	ds_read_b128 v[206:209], v186 offset:2048
	ds_read_b128 v[210:213], v186 offset:3072
	v_lshl_add_u64 v[186:187], s[20:21], 0, v[164:165]
	s_mov_b32 m0, s52
	s_nop 0
	global_load_lds_dwordx4 v[186:187], off
	v_lshl_add_u64 v[186:187], s[20:21], 0, v[132:133]
	s_add_i32 m0, s52, 0x2000
	s_nop 0
	global_load_lds_dwordx4 v[186:187], off
	s_barrier
	s_waitcnt lgkmcnt(0)
	s_setprio 1
	s_waitcnt lgkmcnt(0)
	v_mfma_f32_16x16x32_bf16 v[108:111], v[198:201], v[152:155], v[108:111]
	v_mfma_f32_16x16x32_bf16 v[120:123], v[206:209], v[152:155], v[120:123]
	v_mfma_f32_16x16x32_bf16 v[116:119], v[198:201], v[160:163], v[116:119]
	v_mfma_f32_16x16x32_bf16 v[112:115], v[206:209], v[160:163], v[112:115]
	v_mfma_f32_16x16x32_bf16 v[84:87], v[198:201], v[170:173], v[84:87]
	v_mfma_f32_16x16x32_bf16 v[80:83], v[206:209], v[170:173], v[80:83]
	v_mfma_f32_16x16x32_bf16 v[68:71], v[198:201], v[178:181], v[68:71]
	v_mfma_f32_16x16x32_bf16 v[64:67], v[206:209], v[178:181], v[64:67]
	v_mfma_f32_16x16x32_bf16 v[108:111], v[202:205], v[156:159], v[108:111]
	v_mfma_f32_16x16x32_bf16 v[120:123], v[210:213], v[156:159], v[120:123]
	v_mfma_f32_16x16x32_bf16 v[116:119], v[202:205], v[166:169], v[116:119]
	v_mfma_f32_16x16x32_bf16 v[112:115], v[210:213], v[166:169], v[112:115]
	v_mfma_f32_16x16x32_bf16 v[84:87], v[202:205], v[174:177], v[84:87]
	v_mfma_f32_16x16x32_bf16 v[80:83], v[210:213], v[174:177], v[80:83]
	v_mfma_f32_16x16x32_bf16 v[68:71], v[202:205], v[182:185], v[68:71]
	v_mfma_f32_16x16x32_bf16 v[64:67], v[210:213], v[182:185], v[64:67]
	s_setprio 0
	s_mov_b32 m0, s41
	v_lshl_add_u64 v[186:187], s[16:17], 0, v[164:165]
	s_barrier
	ds_read_b128 v[152:155], v151 offset:49152
	ds_read_b128 v[156:159], v151 offset:50176
	ds_read_b128 v[160:163], v151 offset:51200
	ds_read_b128 v[166:169], v151 offset:52224
	ds_read_b128 v[170:173], v151 offset:53248
	ds_read_b128 v[174:177], v151 offset:54272
	ds_read_b128 v[178:181], v151 offset:55296
	ds_read_b128 v[182:185], v151 offset:56320
	global_load_lds_dwordx4 v[186:187], off
	v_lshl_add_u64 v[186:187], s[16:17], 0, v[132:133]
	s_mov_b32 m0, s42
	s_nop 0
	global_load_lds_dwordx4 v[186:187], off
	s_barrier
	s_waitcnt lgkmcnt(0)
	s_setprio 1
	s_waitcnt lgkmcnt(0)
	v_mfma_f32_16x16x32_bf16 v[60:63], v[96:99], v[152:155], v[60:63]
	v_mfma_f32_16x16x32_bf16 v[56:59], v[142:145], v[152:155], v[56:59]
	v_mfma_f32_16x16x32_bf16 v[52:55], v[96:99], v[160:163], v[52:55]
	v_mfma_f32_16x16x32_bf16 v[48:51], v[142:145], v[160:163], v[48:51]
	v_mfma_f32_16x16x32_bf16 v[28:31], v[96:99], v[170:173], v[28:31]
	v_mfma_f32_16x16x32_bf16 v[24:27], v[142:145], v[170:173], v[24:27]
	v_mfma_f32_16x16x32_bf16 v[20:23], v[96:99], v[178:181], v[20:23]
	v_mfma_f32_16x16x32_bf16 v[16:19], v[142:145], v[178:181], v[16:19]
	v_mfma_f32_16x16x32_bf16 v[60:63], v[138:141], v[156:159], v[60:63]
	v_mfma_f32_16x16x32_bf16 v[56:59], v[146:149], v[156:159], v[56:59]
	v_mfma_f32_16x16x32_bf16 v[52:55], v[138:141], v[166:169], v[52:55]
	v_mfma_f32_16x16x32_bf16 v[48:51], v[146:149], v[166:169], v[48:51]
	v_mfma_f32_16x16x32_bf16 v[28:31], v[138:141], v[174:177], v[28:31]
	v_mfma_f32_16x16x32_bf16 v[24:27], v[146:149], v[174:177], v[24:27]
	v_mfma_f32_16x16x32_bf16 v[20:23], v[138:141], v[182:185], v[20:23]
	v_mfma_f32_16x16x32_bf16 v[16:19], v[146:149], v[182:185], v[16:19]
	s_setprio 0
	s_barrier
	s_add_u32 s14, s14, 0xc000
	s_addc_u32 s15, s15, 0
	s_add_i32 s16, s53, s36
	v_lshl_add_u64 v[96:97], s[14:15], 0, v[164:165]
	s_mov_b32 m0, s16
	s_nop 0
	global_load_lds_dwordx4 v[96:97], off
	v_lshl_add_u64 v[96:97], s[14:15], 0, v[132:133]
	s_add_i32 m0, s16, 0x2000
	s_nop 0
	global_load_lds_dwordx4 v[96:97], off
	s_waitcnt vmcnt(6)
	s_barrier
	s_setprio 1
	v_mfma_f32_16x16x32_bf16 v[44:47], v[198:201], v[152:155], v[44:47]
	v_mfma_f32_16x16x32_bf16 v[40:43], v[206:209], v[152:155], v[40:43]
	v_mfma_f32_16x16x32_bf16 v[36:39], v[198:201], v[160:163], v[36:39]
	v_mfma_f32_16x16x32_bf16 v[32:35], v[206:209], v[160:163], v[32:35]
	v_mfma_f32_16x16x32_bf16 v[12:15], v[198:201], v[170:173], v[12:15]
	v_mfma_f32_16x16x32_bf16 v[8:11], v[206:209], v[170:173], v[8:11]
	v_mfma_f32_16x16x32_bf16 v[4:7], v[198:201], v[178:181], v[4:7]
	v_mfma_f32_16x16x32_bf16 v[0:3], v[206:209], v[178:181], v[0:3]
	v_mfma_f32_16x16x32_bf16 v[44:47], v[202:205], v[156:159], v[44:47]
	v_mfma_f32_16x16x32_bf16 v[40:43], v[210:213], v[156:159], v[40:43]
	v_mfma_f32_16x16x32_bf16 v[36:39], v[202:205], v[166:169], v[36:39]
	v_mfma_f32_16x16x32_bf16 v[32:35], v[210:213], v[166:169], v[32:35]
	v_mfma_f32_16x16x32_bf16 v[12:15], v[202:205], v[174:177], v[12:15]
	v_mfma_f32_16x16x32_bf16 v[8:11], v[210:213], v[174:177], v[8:11]
	v_mfma_f32_16x16x32_bf16 v[4:7], v[202:205], v[182:185], v[4:7]
	v_mfma_f32_16x16x32_bf16 v[0:3], v[210:213], v[182:185], v[0:3]
	s_setprio 0
	s_add_i32 s51, s51, 2
	s_add_u32 s10, s10, 0x10000
	s_addc_u32 s11, s11, 0
	s_add_u32 s48, s48, 0x10000
	s_addc_u32 s50, s50, 0
	s_cmp_gt_u32 s51, 41
	s_barrier
	s_cbranch_scc0 .LBB0_1549
	v_mov_b32_e32 v96, v188
	s_lshl_b32 s11, s47, 8
	v_readfirstlane_b32 s20, v96
	s_lshr_b32 s14, s20, 1
	s_and_b32 s14, s14, 0x60
	v_and_b32_e32 v98, 15, v96
	s_lshl_b32 s10, s46, 8
	s_or_b32 s11, s14, s11
	v_lshrrev_b32_e32 v96, 2, v96
	v_and_or_b32 v96, v96, 12, s11
	s_ashr_i32 s11, s10, 31
	s_add_i32 s16, s10, 0xffffe000
	s_lshl_b64 s[14:15], s[10:11], 12
	s_add_u32 s14, s0, s14
	s_addc_u32 s15, s1, s15
	s_lshr_b32 s11, s16, 12
	s_add_i32 s11, s11, 1
	s_cmp_gt_i32 s46, 31
	s_cselect_b32 s11, s11, 0
	s_mul_hi_u32 s17, s11, 0x6000
	s_mulk_i32 s11, 0x6000
	s_add_u32 s16, s2, s11
	s_addc_u32 s17, s6, s17
	s_ashr_i32 s11, s20, 2
	s_andn2_b32 s11, s11, 63
	v_ashrrev_i32_e32 v97, 31, v96
	v_or_b32_e32 v148, s11, v98
	v_lshlrev_b64 v[142:143], 2, v[96:97]
	v_ashrrev_i32_e32 v149, 31, v148
	v_lshl_add_u64 v[146:147], s[14:15], 0, v[142:143]
	v_lshlrev_b64 v[96:97], 12, v[148:149]
	v_lshl_add_u64 v[138:139], v[146:147], 0, v[96:97]
	v_or_b32_e32 v96, 16, v148
	v_ashrrev_i32_e32 v97, 31, v96
	v_lshlrev_b64 v[96:97], 12, v[96:97]
	v_lshl_add_u64 v[186:187], s[16:17], 0, v[142:143]
	s_add_i32 s11, s11, s10
	v_lshl_add_u64 v[96:97], v[146:147], 0, v[96:97]
	v_or_b32_e32 v144, s11, v98
	global_load_dwordx4 v[152:155], v[138:139], off nt
	global_load_dwordx4 v[156:159], v[138:139], off offset:64 nt
	global_load_dwordx4 v[160:163], v[138:139], off offset:512 nt
	global_load_dwordx4 v[166:169], v[138:139], off offset:576 nt
	global_load_dwordx4 v[170:173], v[96:97], off nt
	global_load_dwordx4 v[174:177], v[96:97], off offset:64 nt
	global_load_dwordx4 v[178:181], v[96:97], off offset:512 nt
	global_load_dwordx4 v[182:185], v[96:97], off offset:576 nt
	v_ashrrev_i32_e32 v145, 31, v144
	global_load_dwordx4 v[96:99], v[186:187], off
	global_load_dwordx4 v[202:205], v[186:187], off offset:64
	global_load_dwordx4 v[206:209], v[186:187], off offset:512
	global_load_dwordx4 v[210:213], v[186:187], off offset:576
	s_mov_b64 s[100:101], 0x20000
	v_lshl_add_u64 v[214:215], v[138:139], 0, s[100:101]
	global_load_dwordx4 v[218:221], v[214:215], off nt
	global_load_dwordx4 v[222:225], v[214:215], off offset:64 nt
	global_load_dwordx4 v[226:229], v[214:215], off offset:512 nt
	global_load_dwordx4 v[230:233], v[214:215], off offset:576 nt
	s_mov_b64 s[100:101], 0x30000
	v_lshl_add_u64 v[216:217], v[138:139], 0, s[100:101]
	global_load_dwordx4 v[240:243], v[216:217], off nt
	global_load_dwordx4 v[244:247], v[216:217], off offset:64 nt
	global_load_dwordx4 v[248:251], v[216:217], off offset:512 nt
	global_load_dwordx4 v[252:255], v[216:217], off offset:576 nt
	v_lshlrev_b64 v[140:141], 12, v[144:145]
	v_lshl_add_u64 v[140:141], s[0:1], 0, v[140:141]
	v_lshl_add_u64 v[140:141], v[140:141], 0, v[142:143]
	s_mov_b32 s10, 0x80000
	s_mov_b64 s[14:15], 0x80000
	s_mov_b32 s11, 0x90000
	s_mov_b64 s[16:17], 0x90000
	v_readlane_b32 s52, v236, 11
	s_mov_b32 s67, 0xb0000
	s_mov_b32 s46, s45
	s_mov_b32 s47, s44
	s_movk_i32 s50, 0x6000
	s_movk_i32 s48, 0x1fff
	v_readlane_b32 s53, v236, 12
	s_mov_b64 s[58:59], 0x1000
	s_waitcnt vmcnt(0)
	v_pk_fma_f32 v[154:155], v[102:103], v[98:99], v[154:155]
	v_pk_fma_f32 v[152:153], v[100:101], v[96:97], v[152:153]
	v_mov_b32_e32 v100, v202
	v_mov_b32_e32 v101, v203
	v_mov_b32_e32 v102, v204
	v_mov_b32_e32 v103, v205
	v_pk_fma_f32 v[158:159], v[106:107], v[102:103], v[158:159]
	v_pk_fma_f32 v[156:157], v[104:105], v[100:101], v[156:157]
	v_mov_b32_e32 v104, v206
	v_mov_b32_e32 v105, v207
	v_mov_b32_e32 v106, v208
	v_mov_b32_e32 v107, v209
	v_pk_fma_f32 v[162:163], v[110:111], v[106:107], v[162:163]
	v_pk_fma_f32 v[160:161], v[108:109], v[104:105], v[160:161]
	v_mov_b32_e32 v108, v210
	v_mov_b32_e32 v109, v211
	v_mov_b32_e32 v110, v212
	v_mov_b32_e32 v111, v213
	s_nop 0
	global_store_dwordx4 v[140:141], v[152:155], off nt
	global_store_dwordx4 v[140:141], v[156:159], off offset:64 nt
	global_store_dwordx4 v[140:141], v[160:163], off offset:512 nt
	v_pk_fma_f32 v[118:119], v[118:119], v[106:107], v[180:181]
	v_pk_fma_f32 v[116:117], v[116:117], v[104:105], v[178:179]
	v_or_b32_e32 v160, 32, v144
	v_ashrrev_i32_e32 v161, 31, v160
	v_lshlrev_b64 v[160:161], 12, v[160:161]
	v_lshl_add_u64 v[160:161], s[0:1], 0, v[160:161]
	v_lshl_add_u64 v[160:161], v[160:161], 0, v[142:143]
	v_pk_fma_f32 v[122:123], v[122:123], v[110:111], v[168:169]
	v_pk_fma_f32 v[120:121], v[120:121], v[108:109], v[166:167]
	global_store_dwordx4 v[140:141], v[120:123], off offset:576 nt
	v_pk_fma_f32 v[114:115], v[114:115], v[110:111], v[184:185]
	v_pk_fma_f32 v[112:113], v[112:113], v[108:109], v[182:183]
	v_or_b32_e32 v120, 16, v144
	v_ashrrev_i32_e32 v121, 31, v120
	v_lshlrev_b64 v[120:121], 12, v[120:121]
	v_lshl_add_u64 v[120:121], s[0:1], 0, v[120:121]
	v_lshl_add_u64 v[152:153], v[120:121], 0, v[142:143]
	global_store_dwordx4 v[152:153], v[112:115], off offset:576 nt
	v_pk_fma_f32 v[122:123], v[130:131], v[98:99], v[172:173]
	v_pk_fma_f32 v[120:121], v[128:129], v[96:97], v[170:171]
	v_or_b32_e32 v112, 32, v148
	v_ashrrev_i32_e32 v113, 31, v112
	global_store_dwordx4 v[152:153], v[120:123], off nt
	v_lshlrev_b64 v[112:113], 12, v[112:113]
	global_store_dwordx4 v[152:153], v[116:119], off offset:512 nt
	v_pk_fma_f32 v[122:123], v[126:127], v[102:103], v[176:177]
	v_pk_fma_f32 v[120:121], v[124:125], v[100:101], v[174:175]
	global_store_dwordx4 v[152:153], v[120:123], off offset:64 nt
	v_lshl_add_u64 v[124:125], v[146:147], 0, v[112:113]
	v_mov_b32_e32 v112, v218
	v_mov_b32_e32 v113, v219
	v_mov_b32_e32 v114, v220
	v_mov_b32_e32 v115, v221
	v_mov_b32_e32 v116, v222
	v_mov_b32_e32 v117, v223
	v_mov_b32_e32 v118, v224
	v_mov_b32_e32 v119, v225
	v_mov_b32_e32 v120, v226
	v_mov_b32_e32 v121, v227
	v_mov_b32_e32 v122, v228
	v_mov_b32_e32 v123, v229
	s_nop 0
	v_mov_b32_e32 v124, v230
	v_mov_b32_e32 v125, v231
	v_mov_b32_e32 v126, v232
	v_mov_b32_e32 v127, v233
	v_or_b32_e32 v128, 48, v148
	v_ashrrev_i32_e32 v129, 31, v128
	v_lshlrev_b64 v[128:129], 12, v[128:129]
	v_lshl_add_u64 v[156:157], v[146:147], 0, v[128:129]
	v_mov_b32_e32 v128, v240
	v_mov_b32_e32 v129, v241
	v_mov_b32_e32 v130, v242
	v_mov_b32_e32 v131, v243
	v_mov_b32_e32 v146, v244
	v_mov_b32_e32 v147, v245
	v_mov_b32_e32 v148, v246
	v_mov_b32_e32 v149, v247
	v_mov_b32_e32 v152, v248
	v_mov_b32_e32 v153, v249
	v_mov_b32_e32 v154, v250
	v_mov_b32_e32 v155, v251
	s_nop 0
	v_mov_b32_e32 v156, v252
	v_mov_b32_e32 v157, v253
	v_mov_b32_e32 v158, v254
	v_mov_b32_e32 v159, v255
	s_mov_b64 s[100:101], 0x80000
	v_lshl_add_u64 v[214:215], v[138:139], 0, s[100:101]
	global_load_dwordx4 v[218:221], v[214:215], off nt
	global_load_dwordx4 v[222:225], v[214:215], off offset:64 nt
	global_load_dwordx4 v[226:229], v[214:215], off offset:512 nt
	global_load_dwordx4 v[230:233], v[214:215], off offset:576 nt
	s_mov_b64 s[100:101], 0x90000
	v_lshl_add_u64 v[216:217], v[138:139], 0, s[100:101]
	global_load_dwordx4 v[240:243], v[216:217], off nt
	global_load_dwordx4 v[244:247], v[216:217], off offset:64 nt
	global_load_dwordx4 v[248:251], v[216:217], off offset:512 nt
	global_load_dwordx4 v[252:255], v[216:217], off offset:576 nt
	v_pk_fma_f32 v[94:95], v[94:95], v[98:99], v[114:115]
	v_pk_fma_f32 v[92:93], v[92:93], v[96:97], v[112:113]
	v_pk_fma_f32 v[90:91], v[90:91], v[102:103], v[118:119]
	v_pk_fma_f32 v[82:83], v[82:83], v[110:111], v[126:127]
	v_pk_fma_f32 v[80:81], v[80:81], v[108:109], v[124:125]
	global_store_dwordx4 v[160:161], v[80:83], off offset:576 nt
	v_pk_fma_f32 v[88:89], v[88:89], v[100:101], v[116:117]
	v_pk_fma_f32 v[86:87], v[86:87], v[106:107], v[122:123]
	v_or_b32_e32 v80, 48, v144
	v_ashrrev_i32_e32 v81, 31, v80
	v_lshlrev_b64 v[80:81], 12, v[80:81]
	v_lshl_add_u64 v[80:81], s[0:1], 0, v[80:81]
	v_lshl_add_u64 v[80:81], v[80:81], 0, v[142:143]
	v_pk_fma_f32 v[66:67], v[66:67], v[110:111], v[158:159]
	v_pk_fma_f32 v[64:65], v[64:65], v[108:109], v[156:157]
	global_store_dwordx4 v[80:81], v[64:67], off offset:576 nt
	v_pk_fma_f32 v[84:85], v[84:85], v[104:105], v[120:121]
	v_pk_fma_f32 v[78:79], v[78:79], v[98:99], v[130:131]
	v_add_co_u32_e32 v64, vcc, s10, v138
	v_pk_fma_f32 v[76:77], v[76:77], v[96:97], v[128:129]
	v_pk_fma_f32 v[74:75], v[74:75], v[102:103], v[148:149]
	v_pk_fma_f32 v[72:73], v[72:73], v[100:101], v[146:147]
	v_pk_fma_f32 v[70:71], v[70:71], v[106:107], v[154:155]
	v_pk_fma_f32 v[68:69], v[68:69], v[104:105], v[152:153]
	v_addc_co_u32_e32 v65, vcc, 0, v139, vcc
	global_store_dwordx4 v[160:161], v[92:95], off nt
	global_store_dwordx4 v[160:161], v[88:91], off offset:64 nt
	global_store_dwordx4 v[160:161], v[84:87], off offset:512 nt
	global_store_dwordx4 v[80:81], v[76:79], off nt
	global_store_dwordx4 v[80:81], v[72:75], off offset:64 nt
	global_store_dwordx4 v[80:81], v[68:71], off offset:512 nt
	v_lshl_add_u64 v[76:77], v[138:139], 0, s[14:15]
	v_add_co_u32_e32 v80, vcc, s11, v138
	s_waitcnt vmcnt(8)
	v_mov_b32_e32 v64, v218
	v_mov_b32_e32 v65, v219
	v_mov_b32_e32 v66, v220
	v_mov_b32_e32 v67, v221
	s_nop 0
	v_mov_b32_e32 v68, v222
	v_mov_b32_e32 v69, v223
	v_mov_b32_e32 v70, v224
	v_mov_b32_e32 v71, v225
	v_mov_b32_e32 v72, v226
	v_mov_b32_e32 v73, v227
	v_mov_b32_e32 v74, v228
	v_mov_b32_e32 v75, v229
	s_nop 0
	v_mov_b32_e32 v76, v230
	v_mov_b32_e32 v77, v231
	v_mov_b32_e32 v78, v232
	v_mov_b32_e32 v79, v233
	v_lshl_add_u64 v[92:93], v[138:139], 0, s[16:17]
	v_addc_co_u32_e32 v81, vcc, 0, v139, vcc
	v_mov_b32_e32 v80, v240
	v_mov_b32_e32 v81, v241
	v_mov_b32_e32 v82, v242
	v_mov_b32_e32 v83, v243
	s_nop 0
	v_mov_b32_e32 v84, v244
	v_mov_b32_e32 v85, v245
	v_mov_b32_e32 v86, v246
	v_mov_b32_e32 v87, v247
	v_mov_b32_e32 v88, v248
	v_mov_b32_e32 v89, v249
	v_mov_b32_e32 v90, v250
	v_mov_b32_e32 v91, v251
	s_nop 0
	v_mov_b32_e32 v92, v252
	v_mov_b32_e32 v93, v253
	v_mov_b32_e32 v94, v254
	v_mov_b32_e32 v95, v255
	s_mov_b64 s[100:101], 0xa0000
	v_lshl_add_u64 v[214:215], v[138:139], 0, s[100:101]
	global_load_dwordx4 v[218:221], v[214:215], off nt
	global_load_dwordx4 v[222:225], v[214:215], off offset:64 nt
	global_load_dwordx4 v[226:229], v[214:215], off offset:512 nt
	global_load_dwordx4 v[230:233], v[214:215], off offset:576 nt
	s_mov_b64 s[100:101], 0xb0000
	v_lshl_add_u64 v[216:217], v[138:139], 0, s[100:101]
	global_load_dwordx4 v[240:243], v[216:217], off nt
	global_load_dwordx4 v[244:247], v[216:217], off offset:64 nt
	global_load_dwordx4 v[248:251], v[216:217], off offset:512 nt
	global_load_dwordx4 v[252:255], v[216:217], off offset:576 nt
	v_lshl_add_u64 v[112:113], v[140:141], 0, s[14:15]
	s_mov_b64 s[14:15], 0xa0000
	v_pk_fma_f32 v[60:61], v[60:61], v[96:97], v[64:65]
	v_add_co_u32_e32 v64, vcc, s10, v140
	v_pk_fma_f32 v[46:47], v[46:47], v[106:107], v[74:75]
	s_nop 0
	v_addc_co_u32_e32 v65, vcc, 0, v141, vcc
	v_pk_fma_f32 v[44:45], v[44:45], v[104:105], v[72:73]
	global_store_dwordx4 v[112:113], v[44:47], off offset:512 nt
	v_pk_fma_f32 v[42:43], v[42:43], v[110:111], v[78:79]
	v_pk_fma_f32 v[40:41], v[40:41], v[108:109], v[76:77]
	v_add_co_u32_e32 v46, vcc, s11, v140
	global_store_dwordx4 v[112:113], v[40:43], off offset:576 nt
	v_lshl_add_u64 v[44:45], v[140:141], 0, s[16:17]
	v_addc_co_u32_e32 v47, vcc, 0, v141, vcc
	v_pk_fma_f32 v[42:43], v[54:55], v[98:99], v[82:83]
	v_pk_fma_f32 v[40:41], v[52:53], v[96:97], v[80:81]
	v_pk_fma_f32 v[34:35], v[34:35], v[110:111], v[94:95]
	v_pk_fma_f32 v[32:33], v[32:33], v[108:109], v[92:93]
	s_mov_b32 s10, 0xa0000
	v_pk_fma_f32 v[62:63], v[62:63], v[98:99], v[66:67]
	v_pk_fma_f32 v[58:59], v[58:59], v[102:103], v[70:71]
	v_pk_fma_f32 v[56:57], v[56:57], v[100:101], v[68:69]
	global_store_dwordx4 v[46:47], v[40:43], off nt
	v_pk_fma_f32 v[38:39], v[38:39], v[106:107], v[90:91]
	v_pk_fma_f32 v[36:37], v[36:37], v[104:105], v[88:89]
	v_pk_fma_f32 v[42:43], v[50:51], v[102:103], v[86:87]
	v_pk_fma_f32 v[40:41], v[48:49], v[100:101], v[84:85]
	global_store_dwordx4 v[44:45], v[32:35], off offset:576 nt
	global_store_dwordx4 v[64:65], v[60:63], off nt
	global_store_dwordx4 v[112:113], v[56:59], off offset:64 nt
	v_add_co_u32_e32 v32, vcc, s10, v138
	global_store_dwordx4 v[44:45], v[40:43], off offset:64 nt
	global_store_dwordx4 v[44:45], v[36:39], off offset:512 nt
	v_lshl_add_u64 v[44:45], v[138:139], 0, s[14:15]
	v_addc_co_u32_e32 v33, vcc, 0, v139, vcc
	s_mov_b32 s11, 0xb0000
	s_waitcnt vmcnt(8)
	v_mov_b32_e32 v32, v218
	v_mov_b32_e32 v33, v219
	v_mov_b32_e32 v34, v220
	v_mov_b32_e32 v35, v221
	s_nop 0
	v_mov_b32_e32 v36, v222
	v_mov_b32_e32 v37, v223
	v_mov_b32_e32 v38, v224
	v_mov_b32_e32 v39, v225
	v_mov_b32_e32 v40, v226
	v_mov_b32_e32 v41, v227
	v_mov_b32_e32 v42, v228
	v_mov_b32_e32 v43, v229
	s_nop 0
	v_mov_b32_e32 v44, v230
	v_mov_b32_e32 v45, v231
	v_mov_b32_e32 v46, v232
	v_mov_b32_e32 v47, v233
	s_mov_b64 s[16:17], 0xb0000
	v_add_co_u32_e32 v48, vcc, s11, v138
	v_lshl_add_u64 v[60:61], v[138:139], 0, s[16:17]
	s_nop 0
	v_addc_co_u32_e32 v49, vcc, 0, v139, vcc
	v_mov_b32_e32 v48, v240
	v_mov_b32_e32 v49, v241
	v_mov_b32_e32 v50, v242
	v_mov_b32_e32 v51, v243
	s_nop 0
	v_mov_b32_e32 v52, v244
	v_mov_b32_e32 v53, v245
	v_mov_b32_e32 v54, v246
	v_mov_b32_e32 v55, v247
	v_mov_b32_e32 v56, v248
	v_mov_b32_e32 v57, v249
	v_mov_b32_e32 v58, v250
	v_mov_b32_e32 v59, v251
	s_nop 0
	v_mov_b32_e32 v60, v252
	v_mov_b32_e32 v61, v253
	v_mov_b32_e32 v62, v254
	v_mov_b32_e32 v63, v255
	v_lshl_add_u64 v[64:65], v[140:141], 0, s[14:15]
	s_mov_b64 s[14:15], s[8:9]
	v_pk_fma_f32 v[28:29], v[28:29], v[96:97], v[32:33]
	v_add_co_u32_e32 v32, vcc, s10, v140
	v_pk_fma_f32 v[14:15], v[14:15], v[106:107], v[42:43]
	s_nop 0
	v_addc_co_u32_e32 v33, vcc, 0, v141, vcc
	v_pk_fma_f32 v[12:13], v[12:13], v[104:105], v[40:41]
	global_store_dwordx4 v[64:65], v[12:15], off offset:512 nt
	v_pk_fma_f32 v[10:11], v[10:11], v[110:111], v[46:47]
	v_pk_fma_f32 v[8:9], v[8:9], v[108:109], v[44:45]
	v_add_co_u32_e32 v14, vcc, s11, v140
	global_store_dwordx4 v[64:65], v[8:11], off offset:576 nt
	s_nop 0
	v_addc_co_u32_e32 v15, vcc, 0, v141, vcc
	v_pk_fma_f32 v[10:11], v[22:23], v[98:99], v[50:51]
	v_pk_fma_f32 v[8:9], v[20:21], v[96:97], v[48:49]
	v_pk_fma_f32 v[30:31], v[30:31], v[98:99], v[34:35]
	v_pk_fma_f32 v[26:27], v[26:27], v[102:103], v[38:39]
	v_pk_fma_f32 v[24:25], v[24:25], v[100:101], v[36:37]
	v_lshl_add_u64 v[12:13], v[140:141], 0, s[16:17]
	global_store_dwordx4 v[14:15], v[8:11], off nt
	v_pk_fma_f32 v[6:7], v[6:7], v[106:107], v[58:59]
	v_pk_fma_f32 v[4:5], v[4:5], v[104:105], v[56:57]
	v_pk_fma_f32 v[10:11], v[18:19], v[102:103], v[54:55]
	v_pk_fma_f32 v[8:9], v[16:17], v[100:101], v[52:53]
	v_pk_fma_f32 v[2:3], v[2:3], v[110:111], v[62:63]
	v_pk_fma_f32 v[0:1], v[0:1], v[108:109], v[60:61]
	s_and_b64 vcc, exec, s[12:13]
	s_mov_b32 s12, s45
	s_mov_b32 s13, s44
	s_mov_b64 s[10:11], s[4:5]
	v_readlane_b32 s44, v236, 3
	global_store_dwordx4 v[32:33], v[28:31], off nt
	global_store_dwordx4 v[64:65], v[24:27], off offset:64 nt
	global_store_dwordx4 v[12:13], v[8:11], off offset:64 nt
	global_store_dwordx4 v[12:13], v[4:7], off offset:512 nt
	global_store_dwordx4 v[12:13], v[0:3], off offset:576 nt
	v_readlane_b32 s45, v236, 4
	s_cbranch_vccz .LBB0_1541
	s_branch .LBB0_1555
